# ph9 GEMM tail: 64 tail tiles run as 128 half tiles (128 rows) on workgroups 0..127, ai=1 MFMAs/stores skipped in half mode
# speedup vs baseline: 1.0235x; 1.0124x over previous
.LBB0_246:
	v_readlane_b32 s2, v255, 31
	v_readlane_b32 s3, v255, 32
	s_add_u32 s2, s18, 0x8800000
	s_mov_b32 s47, s3
	s_addc_u32 s3, s19, 0
	s_mul_i32 s46, s8, 0xd800
	s_add_u32 s30, s18, 0x5e00000
	s_addc_u32 s31, s19, 0
	s_mov_b32 s43, s47
	s_lshl_b64 s[46:47], s[46:47], 2
	s_add_u32 s18, s18, s46
	s_addc_u32 s19, s19, s47
	s_add_u32 s62, s18, 0x5d00000
	s_addc_u32 s63, s19, 0
	s_ashr_i32 s18, s35, 31
	s_lshr_b32 s18, s18, 26
	s_add_i32 s18, s35, s18
	v_writelane_b32 v255, s42, 31
	s_ashr_i32 s67, s18, 6
	s_lshl_b32 s18, s37, 12
	v_writelane_b32 v255, s43, 32
	s_lshl_b32 s42, s42, 13
	s_and_b32 s37, s18, 0x3000
	s_add_u32 s18, s26, 0x80
	v_mov_b32_e32 v173, v1
	s_addc_u32 s19, s27, 0
	s_waitcnt vmcnt(2)
	s_barrier
	s_add_i32 m0, s40, 0x18000
	v_lshl_add_u64 v[2:3], s[18:19], 0, v[172:173]
	v_mov_b32_e32 v171, v1
	global_load_lds_dwordx4 v[2:3], off
	s_add_i32 m0, s40, 0x1a000
	v_lshl_add_u64 v[2:3], s[18:19], 0, v[170:171]
	s_add_u32 s18, s56, 0x80
	s_addc_u32 s19, s57, 0
	s_add_i32 s68, s40, 0x8000
	global_load_lds_dwordx4 v[2:3], off
	s_mov_b32 m0, s68
	v_lshl_add_u64 v[2:3], s[18:19], 0, v[172:173]
	s_add_i32 s69, s40, 0xa000
	global_load_lds_dwordx4 v[2:3], off
	v_lshl_add_u64 v[2:3], s[18:19], 0, v[170:171]
	s_add_u32 s18, s26, 0x40080
	s_mov_b32 m0, s69
	s_addc_u32 s19, s27, 0
	global_load_lds_dwordx4 v[2:3], off
	s_add_i32 m0, s40, 0x1c000
	v_lshl_add_u64 v[2:3], s[18:19], 0, v[172:173]
	global_load_lds_dwordx4 v[2:3], off
	v_lshl_add_u64 v[2:3], s[18:19], 0, v[170:171]
	s_add_i32 m0, s40, 0x1e000
	s_cmp_gt_i32 s35, 63
	global_load_lds_dwordx4 v[2:3], off
	v_and_b32_e32 v2, 15, v0
	v_and_b32_e32 v3, 48, v0
	v_lshlrev_b32_e32 v2, 6, v2
	v_lshlrev_b32_e32 v0, 2, v0
	s_sext_i32_i8 s45, s34
	v_or_b32_e32 v4, v2, v3
	v_and_b32_e32 v0, 32, v0
	s_waitcnt vmcnt(6)
	s_cselect_b64 s[34:35], -1, 0
	s_add_i32 s70, s67, -2
	v_bitop3_b32 v2, v2, v0, v3 bitop3:0x36
	v_bitop3_b32 v0, v4, s42, v0 bitop3:0xde
	s_cmpk_lt_u32 s36, 0x100
	v_or_b32_e32 v213, s37, v2
	s_cselect_b64 s[36:37], -1, 0
	s_mov_b32 s71, 0
	s_mov_b32 s100, 0
	s_mov_b32 s101, 0
	v_add_u32_e32 v216, 0, v0
	s_barrier
	s_branch .LBB0_249

.LBB0_248:
	s_mov_b32 s100, s101
	s_andn2_b64 vcc, exec, s[18:19]
	s_mov_b32 s45, s46
	s_mov_b32 s44, s48
	s_mov_b64 s[26:27], s[54:55]
	s_mov_b64 s[56:57], s[50:51]
	s_cbranch_vccz .LBB0_260
.LBB0_249:
	s_add_i32 s71, s71, 1
	s_mul_i32 s18, s71, s15
	s_mul_hi_u32 s19, s71, s64
	s_add_i32 s19, s19, s18
	s_mul_i32 s18, s71, s64
	s_add_u32 s18, s18, s16
	s_addc_u32 s19, s19, s39
	s_mov_b32 s101, 0
	s_cmp_lg_u32 s71, 1
	s_cbranch_scc1 .Lh9_a
	s_movk_i32 s18, 0x140
	s_mov_b32 s19, 0
	s_cmp_gt_i32 s16, 0x7f
	s_cbranch_scc1 .Lh9_a
	s_and_b32 s101, s16, 1
	s_add_i32 s101, s101, 1
	s_lshr_b32 s18, s16, 1
	s_addk_i32 s18, 0x100
.Lh9_a:
	v_cmp_gt_i64_e32 vcc, s[18:19], v[176:177]
	v_cmp_lt_i64_e64 s[42:43], s[18:19], v[174:175]
	s_cbranch_vccnz .LBB0_251
	s_ashr_i32 s19, s18, 31
	s_lshr_b32 s19, s19, 29
	s_add_i32 s19, s18, s19
	s_ashr_i32 s46, s19, 3
	s_and_b32 s19, s19, -8
	s_sub_i32 s18, s18, s19
	s_cmp_lt_i32 s18, 0
	s_cselect_b32 s19, 41, 40
	s_mul_i32 s18, s19, s18
	s_add_i32 s18, s18, s46
	s_ashr_i32 s19, s18, 31
	s_lshr_b32 s19, s19, 28
	s_add_i32 s19, s18, s19
	s_ashr_i32 s46, s19, 4
	s_lshl_b32 s47, s46, 2
	s_sub_i32 s46, 0x50, s47
	s_min_i32 s48, s46, 4
	s_abs_i32 s46, s48
	v_cvt_f32_u32_e32 v0, s46
	s_sub_i32 s50, 0, s46
	s_and_b32 s19, s19, -16
	s_sub_i32 s18, s18, s19
	v_rcp_iflag_f32_e32 v0, v0
	s_abs_i32 s19, s18
	s_xor_b32 s49, s18, s48
	s_ashr_i32 s49, s49, 31
	v_mul_f32_e32 v0, 0x4f7ffffe, v0
	v_cvt_u32_f32_e32 v0, v0
	s_nop 0
	v_readfirstlane_b32 s51, v0
	s_mul_i32 s50, s50, s51
	s_mul_hi_u32 s50, s51, s50
	s_add_i32 s51, s51, s50
	s_mul_hi_u32 s50, s19, s51
	s_mul_i32 s51, s50, s46
	s_sub_i32 s19, s19, s51
	s_add_i32 s54, s50, 1
	s_sub_i32 s51, s19, s46
	s_cmp_ge_u32 s19, s46
	s_cselect_b32 s50, s54, s50
	s_cselect_b32 s19, s51, s19
	s_add_i32 s51, s50, 1
	s_cmp_ge_u32 s19, s46
	s_cselect_b32 s19, s51, s50
	s_xor_b32 s19, s19, s49
	s_sub_i32 s46, s19, s49
	s_mul_i32 s19, s46, s48
	s_sub_i32 s18, s18, s19
	s_add_i32 s48, s18, s47
.LBB0_251:
	s_ashr_i32 s49, s48, 31
	s_lshl_b64 s[18:19], s[48:49], 19
	s_add_u32 s50, s17, s18
	s_addc_u32 s51, s21, s19
	s_cmp_lg_u32 s101, 2
	s_cbranch_scc1 .Lh9_b
	s_add_u32 s50, s50, 0x40000
	s_addc_u32 s51, s51, 0
.Lh9_b:
	s_ashr_i32 s47, s46, 31
	s_lshl_b64 s[18:19], s[46:47], 19
	s_add_u32 s54, s22, s18
	v_mov_b32_e32 v129, 0
	s_addc_u32 s55, s23, s19
	s_andn2_b64 vcc, exec, s[34:35]
	s_cbranch_vccnz .LBB0_255
	s_and_b64 s[18:19], s[42:43], exec
	s_cselect_b32 s47, s51, s57
	s_cselect_b32 s49, s50, s56
	s_cselect_b32 s72, s55, s27
	s_cselect_b32 s73, s54, s26
	s_add_u32 s78, s56, 0x100
	s_addc_u32 s79, s57, 0
	s_add_u32 s80, s26, 0x100
	v_mov_b32_e32 v2, 0
	s_addc_u32 s81, s27, 0
	s_mov_b32 s18, 0
	v_mov_b32_e32 v3, v2
	v_mov_b32_e32 v4, v2
	v_mov_b32_e32 v5, v2
	v_mov_b32_e32 v6, v2
	v_mov_b32_e32 v7, v2
	v_mov_b32_e32 v8, v2
	v_mov_b32_e32 v9, v2
	v_mov_b32_e32 v18, v2
	v_mov_b32_e32 v19, v2
	v_mov_b32_e32 v20, v2
	v_mov_b32_e32 v21, v2
	v_mov_b32_e32 v22, v2
	v_mov_b32_e32 v23, v2
	v_mov_b32_e32 v24, v2
	v_mov_b32_e32 v25, v2
	v_mov_b32_e32 v34, v2
	v_mov_b32_e32 v35, v2
	v_mov_b32_e32 v36, v2
	v_mov_b32_e32 v37, v2
	v_mov_b32_e32 v38, v2
	v_mov_b32_e32 v39, v2
	v_mov_b32_e32 v40, v2
	v_mov_b32_e32 v41, v2
	v_mov_b32_e32 v50, v2
	v_mov_b32_e32 v51, v2
	v_mov_b32_e32 v52, v2
	v_mov_b32_e32 v53, v2
	v_mov_b32_e32 v54, v2
	v_mov_b32_e32 v55, v2
	v_mov_b32_e32 v56, v2
	v_mov_b32_e32 v57, v2
	v_mov_b32_e32 v10, v2
	v_mov_b32_e32 v11, v2
	v_mov_b32_e32 v12, v2
	v_mov_b32_e32 v13, v2
	v_mov_b32_e32 v14, v2
	v_mov_b32_e32 v15, v2
	v_mov_b32_e32 v16, v2
	v_mov_b32_e32 v17, v2
	v_mov_b32_e32 v26, v2
	v_mov_b32_e32 v27, v2
	v_mov_b32_e32 v28, v2
	v_mov_b32_e32 v29, v2
	v_mov_b32_e32 v30, v2
	v_mov_b32_e32 v31, v2
	v_mov_b32_e32 v32, v2
	v_mov_b32_e32 v33, v2
	v_mov_b32_e32 v42, v2
	v_mov_b32_e32 v43, v2
	v_mov_b32_e32 v44, v2
	v_mov_b32_e32 v45, v2
	v_mov_b32_e32 v46, v2
	v_mov_b32_e32 v47, v2
	v_mov_b32_e32 v48, v2
	v_mov_b32_e32 v49, v2
	v_mov_b32_e32 v58, v2
	v_mov_b32_e32 v59, v2
	v_mov_b32_e32 v60, v2
	v_mov_b32_e32 v61, v2
	v_mov_b32_e32 v62, v2
	v_mov_b32_e32 v63, v2
	v_mov_b32_e32 v64, v2
	v_mov_b32_e32 v65, v2
	v_mov_b32_e32 v66, v2
	v_mov_b32_e32 v67, v2
	v_mov_b32_e32 v68, v2
	v_mov_b32_e32 v69, v2
	v_mov_b32_e32 v70, v2
	v_mov_b32_e32 v71, v2
	v_mov_b32_e32 v72, v2
	v_mov_b32_e32 v73, v2
	v_mov_b32_e32 v82, v2
	v_mov_b32_e32 v83, v2
	v_mov_b32_e32 v84, v2
	v_mov_b32_e32 v85, v2
	v_mov_b32_e32 v86, v2
	v_mov_b32_e32 v87, v2
	v_mov_b32_e32 v88, v2
	v_mov_b32_e32 v89, v2
	v_mov_b32_e32 v98, v2
	v_mov_b32_e32 v99, v2
	v_mov_b32_e32 v100, v2
	v_mov_b32_e32 v101, v2
	v_mov_b32_e32 v102, v2
	v_mov_b32_e32 v103, v2
	v_mov_b32_e32 v104, v2
	v_mov_b32_e32 v105, v2
	v_mov_b32_e32 v114, v2
	v_mov_b32_e32 v115, v2
	v_mov_b32_e32 v116, v2
	v_mov_b32_e32 v117, v2
	v_mov_b32_e32 v118, v2
	v_mov_b32_e32 v119, v2
	v_mov_b32_e32 v120, v2
	v_mov_b32_e32 v121, v2
	v_mov_b32_e32 v74, v2
	v_mov_b32_e32 v75, v2
	v_mov_b32_e32 v76, v2
	v_mov_b32_e32 v77, v2
	v_mov_b32_e32 v78, v2
	v_mov_b32_e32 v79, v2
	v_mov_b32_e32 v80, v2
	v_mov_b32_e32 v81, v2
	v_mov_b32_e32 v90, v2
	v_mov_b32_e32 v91, v2
	v_mov_b32_e32 v92, v2
	v_mov_b32_e32 v93, v2
	v_mov_b32_e32 v94, v2
	v_mov_b32_e32 v95, v2
	v_mov_b32_e32 v96, v2
	v_mov_b32_e32 v97, v2
	v_mov_b32_e32 v106, v2
	v_mov_b32_e32 v107, v2
	v_mov_b32_e32 v108, v2
	v_mov_b32_e32 v109, v2
	v_mov_b32_e32 v110, v2
	v_mov_b32_e32 v111, v2
	v_mov_b32_e32 v112, v2
	v_mov_b32_e32 v113, v2
	v_mov_b32_e32 v122, v2
	v_mov_b32_e32 v123, v2
	v_mov_b32_e32 v124, v2
	v_mov_b32_e32 v125, v2
	v_mov_b32_e32 v126, v2
	v_mov_b32_e32 v127, v2
	v_mov_b32_e32 v128, v2
	v_mov_b32_e32 v129, v2
.LBB0_253:
	s_add_i32 s82, s18, 2
	s_cmp_eq_u32 s70, s18
	s_cselect_b32 s18, s49, s78
	s_cselect_b32 s19, s47, s79
	s_cselect_b32 s56, s73, s80
	s_cselect_b32 s57, s72, s81
	s_add_u32 s26, s18, 0x80
	s_addc_u32 s27, s19, 0
	s_add_i32 s83, 0, 0x10000
	v_add_u32_e32 v0, s83, v213
	s_add_i32 s86, 0, 0x14000
	ds_read_b128 v[130:133], v0
	ds_read_b128 v[134:137], v0 offset:1024
	ds_read_b128 v[138:141], v0 offset:2048
	ds_read_b128 v[142:145], v0 offset:3072
	v_add_u32_e32 v0, s86, v213
	ds_read_b128 v[146:149], v0
	ds_read_b128 v[150:153], v0 offset:1024
	ds_read_b128 v[154:157], v0 offset:2048
	ds_read_b128 v[158:161], v0 offset:3072
	s_add_u32 s84, s78, 0x3ff80
	s_addc_u32 s85, s79, 0
	ds_read_b128 v[162:165], v216
	ds_read_b128 v[166:169], v216 offset:1024
	ds_read_b128 v[194:197], v216 offset:2048
	ds_read_b128 v[198:201], v216 offset:3072
	ds_read_b128 v[202:205], v216 offset:4096
	ds_read_b128 v[206:209], v216 offset:5120
	ds_read_b128 v[218:221], v216 offset:6144
	ds_read_b128 v[222:225], v216 offset:7168
	s_add_i32 m0, s40, 0xc000
	v_lshl_add_u64 v[210:211], s[84:85], 0, v[172:173]
	global_load_lds_dwordx4 v[210:211], off
	v_lshl_add_u64 v[210:211], s[84:85], 0, v[170:171]
	s_add_i32 m0, s40, 0xe000
	s_nop 0
	global_load_lds_dwordx4 v[210:211], off
	s_waitcnt vmcnt(8)
	s_waitcnt lgkmcnt(0)
	s_barrier
	s_setprio 1
	s_waitcnt lgkmcnt(0)
	v_mfma_f32_16x16x32_bf16 v[126:129], v[130:133], v[162:165], v[126:129]
	v_mfma_f32_16x16x32_bf16 v[122:125], v[138:141], v[162:165], v[122:125]
	v_mfma_f32_16x16x32_bf16 v[110:113], v[130:133], v[194:197], v[110:113]
	v_mfma_f32_16x16x32_bf16 v[106:109], v[138:141], v[194:197], v[106:109]
	v_mfma_f32_16x16x32_bf16 v[94:97], v[130:133], v[202:205], v[94:97]
	v_mfma_f32_16x16x32_bf16 v[90:93], v[138:141], v[202:205], v[90:93]
	v_mfma_f32_16x16x32_bf16 v[78:81], v[130:133], v[218:221], v[78:81]
	v_mfma_f32_16x16x32_bf16 v[74:77], v[138:141], v[218:221], v[74:77]
	v_mfma_f32_16x16x32_bf16 v[126:129], v[134:137], v[166:169], v[126:129]
	v_mfma_f32_16x16x32_bf16 v[122:125], v[142:145], v[166:169], v[122:125]
	v_mfma_f32_16x16x32_bf16 v[110:113], v[134:137], v[198:201], v[110:113]
	v_mfma_f32_16x16x32_bf16 v[106:109], v[142:145], v[198:201], v[106:109]
	v_mfma_f32_16x16x32_bf16 v[94:97], v[134:137], v[206:209], v[94:97]
	v_mfma_f32_16x16x32_bf16 v[90:93], v[142:145], v[206:209], v[90:93]
	v_mfma_f32_16x16x32_bf16 v[78:81], v[134:137], v[222:225], v[78:81]
	v_mfma_f32_16x16x32_bf16 v[74:77], v[142:145], v[222:225], v[74:77]
	v_mfma_f32_16x16x32_bf16 v[118:121], v[146:149], v[162:165], v[118:121]
	v_mfma_f32_16x16x32_bf16 v[114:117], v[154:157], v[162:165], v[114:117]
	v_mfma_f32_16x16x32_bf16 v[102:105], v[146:149], v[194:197], v[102:105]
	v_mfma_f32_16x16x32_bf16 v[98:101], v[154:157], v[194:197], v[98:101]
	v_mfma_f32_16x16x32_bf16 v[86:89], v[146:149], v[202:205], v[86:89]
	v_mfma_f32_16x16x32_bf16 v[82:85], v[154:157], v[202:205], v[82:85]
	v_mfma_f32_16x16x32_bf16 v[70:73], v[146:149], v[218:221], v[70:73]
	v_mfma_f32_16x16x32_bf16 v[66:69], v[154:157], v[218:221], v[66:69]
	v_mfma_f32_16x16x32_bf16 v[118:121], v[150:153], v[166:169], v[118:121]
	v_mfma_f32_16x16x32_bf16 v[114:117], v[158:161], v[166:169], v[114:117]
	v_mfma_f32_16x16x32_bf16 v[102:105], v[150:153], v[198:201], v[102:105]
	v_mfma_f32_16x16x32_bf16 v[98:101], v[158:161], v[198:201], v[98:101]
	v_mfma_f32_16x16x32_bf16 v[86:89], v[150:153], v[206:209], v[86:89]
	v_mfma_f32_16x16x32_bf16 v[82:85], v[158:161], v[206:209], v[82:85]
	v_mfma_f32_16x16x32_bf16 v[70:73], v[150:153], v[222:225], v[70:73]
	v_mfma_f32_16x16x32_bf16 v[66:69], v[158:161], v[222:225], v[66:69]
	s_setprio 0
	s_barrier
	s_mov_b64 s[84:85], s[56:57]
	s_add_i32 s83, s83, s25
	ds_read_b128 v[162:165], v216 offset:16384
	ds_read_b128 v[166:169], v216 offset:17408
	ds_read_b128 v[194:197], v216 offset:18432
	ds_read_b128 v[198:201], v216 offset:19456
	ds_read_b128 v[202:205], v216 offset:20480
	ds_read_b128 v[206:209], v216 offset:21504
	ds_read_b128 v[218:221], v216 offset:22528
	ds_read_b128 v[222:225], v216 offset:23552
	s_mov_b32 m0, s83
	v_lshl_add_u64 v[210:211], s[84:85], 0, v[172:173]
	global_load_lds_dwordx4 v[210:211], off
	s_add_i32 m0, s83, 0x2000
	v_lshl_add_u64 v[210:211], s[84:85], 0, v[170:171]
	s_add_u32 s84, s56, 0x40000
	s_addc_u32 s85, s57, 0
	s_add_i32 s83, s86, s25
	global_load_lds_dwordx4 v[210:211], off
	s_mov_b32 m0, s83
	v_lshl_add_u64 v[210:211], s[84:85], 0, v[172:173]
	global_load_lds_dwordx4 v[210:211], off
	v_lshl_add_u64 v[210:211], s[84:85], 0, v[170:171]
	s_add_i32 m0, s83, 0x2000
	s_mov_b64 s[84:85], s[18:19]
	global_load_lds_dwordx4 v[210:211], off
	s_mov_b32 m0, s40
	v_lshl_add_u64 v[210:211], s[84:85], 0, v[172:173]
	global_load_lds_dwordx4 v[210:211], off
	v_lshl_add_u64 v[210:211], s[84:85], 0, v[170:171]
	s_mov_b32 m0, s41
	s_nop 0
	global_load_lds_dwordx4 v[210:211], off
	s_waitcnt vmcnt(8)
	s_waitcnt lgkmcnt(0)
	s_barrier
	s_setprio 1
	s_waitcnt lgkmcnt(0)
	s_cmp_lg_u32 s100, 0
	s_cbranch_scc1 .Lh9_m0
	v_mfma_f32_16x16x32_bf16 v[62:65], v[130:133], v[162:165], v[62:65]
	v_mfma_f32_16x16x32_bf16 v[58:61], v[138:141], v[162:165], v[58:61]
	v_mfma_f32_16x16x32_bf16 v[46:49], v[130:133], v[194:197], v[46:49]
	v_mfma_f32_16x16x32_bf16 v[42:45], v[138:141], v[194:197], v[42:45]
	v_mfma_f32_16x16x32_bf16 v[30:33], v[130:133], v[202:205], v[30:33]
	v_mfma_f32_16x16x32_bf16 v[26:29], v[138:141], v[202:205], v[26:29]
	v_mfma_f32_16x16x32_bf16 v[14:17], v[130:133], v[218:221], v[14:17]
	v_mfma_f32_16x16x32_bf16 v[10:13], v[138:141], v[218:221], v[10:13]
	v_mfma_f32_16x16x32_bf16 v[62:65], v[134:137], v[166:169], v[62:65]
	v_mfma_f32_16x16x32_bf16 v[58:61], v[142:145], v[166:169], v[58:61]
	v_mfma_f32_16x16x32_bf16 v[46:49], v[134:137], v[198:201], v[46:49]
	v_mfma_f32_16x16x32_bf16 v[42:45], v[142:145], v[198:201], v[42:45]
	v_mfma_f32_16x16x32_bf16 v[30:33], v[134:137], v[206:209], v[30:33]
	v_mfma_f32_16x16x32_bf16 v[26:29], v[142:145], v[206:209], v[26:29]
	v_mfma_f32_16x16x32_bf16 v[14:17], v[134:137], v[222:225], v[14:17]
	v_mfma_f32_16x16x32_bf16 v[10:13], v[142:145], v[222:225], v[10:13]
	v_mfma_f32_16x16x32_bf16 v[54:57], v[146:149], v[162:165], v[54:57]
	v_mfma_f32_16x16x32_bf16 v[50:53], v[154:157], v[162:165], v[50:53]
	v_mfma_f32_16x16x32_bf16 v[38:41], v[146:149], v[194:197], v[38:41]
	v_mfma_f32_16x16x32_bf16 v[34:37], v[154:157], v[194:197], v[34:37]
	v_mfma_f32_16x16x32_bf16 v[22:25], v[146:149], v[202:205], v[22:25]
	v_mfma_f32_16x16x32_bf16 v[18:21], v[154:157], v[202:205], v[18:21]
	v_mfma_f32_16x16x32_bf16 v[6:9], v[146:149], v[218:221], v[6:9]
	v_mfma_f32_16x16x32_bf16 v[2:5], v[154:157], v[218:221], v[2:5]
	v_mfma_f32_16x16x32_bf16 v[54:57], v[150:153], v[166:169], v[54:57]
	v_mfma_f32_16x16x32_bf16 v[50:53], v[158:161], v[166:169], v[50:53]
	v_mfma_f32_16x16x32_bf16 v[38:41], v[150:153], v[198:201], v[38:41]
	v_mfma_f32_16x16x32_bf16 v[34:37], v[158:161], v[198:201], v[34:37]
	v_mfma_f32_16x16x32_bf16 v[22:25], v[150:153], v[206:209], v[22:25]
	v_mfma_f32_16x16x32_bf16 v[18:21], v[158:161], v[206:209], v[18:21]
	v_mfma_f32_16x16x32_bf16 v[6:9], v[150:153], v[222:225], v[6:9]
	v_mfma_f32_16x16x32_bf16 v[2:5], v[158:161], v[222:225], v[2:5]
.Lh9_m0:
	s_setprio 0
	s_barrier
	s_add_i32 s83, 0, 0x18000
	v_add_u32_e32 v0, s83, v213
	s_add_i32 s84, 0, 0x1c000
	ds_read_b128 v[130:133], v0
	ds_read_b128 v[134:137], v0 offset:1024
	ds_read_b128 v[138:141], v0 offset:2048
	ds_read_b128 v[142:145], v0 offset:3072
	v_add_u32_e32 v0, s84, v213
	ds_read_b128 v[146:149], v0
	ds_read_b128 v[150:153], v0 offset:1024
	ds_read_b128 v[154:157], v0 offset:2048
	ds_read_b128 v[158:161], v0 offset:3072
	s_add_u32 s18, s18, 0x40000
	s_addc_u32 s19, s19, 0
	s_mov_b32 m0, s60
	ds_read_b128 v[162:165], v216 offset:32768
	ds_read_b128 v[166:169], v216 offset:33792
	ds_read_b128 v[194:197], v216 offset:34816
	ds_read_b128 v[198:201], v216 offset:35840
	ds_read_b128 v[202:205], v216 offset:36864
	ds_read_b128 v[206:209], v216 offset:37888
	ds_read_b128 v[218:221], v216 offset:38912
	ds_read_b128 v[222:225], v216 offset:39936
	s_nop 0
	v_lshl_add_u64 v[210:211], s[18:19], 0, v[172:173]
	global_load_lds_dwordx4 v[210:211], off
	v_lshl_add_u64 v[210:211], s[18:19], 0, v[170:171]
	s_mov_b32 m0, s61
	s_nop 0
	global_load_lds_dwordx4 v[210:211], off
	s_waitcnt vmcnt(8)
	s_waitcnt lgkmcnt(0)
	s_barrier
	s_setprio 1
	s_waitcnt lgkmcnt(0)
	v_mfma_f32_16x16x32_bf16 v[126:129], v[130:133], v[162:165], v[126:129]
	v_mfma_f32_16x16x32_bf16 v[122:125], v[138:141], v[162:165], v[122:125]
	v_mfma_f32_16x16x32_bf16 v[110:113], v[130:133], v[194:197], v[110:113]
	v_mfma_f32_16x16x32_bf16 v[106:109], v[138:141], v[194:197], v[106:109]
	v_mfma_f32_16x16x32_bf16 v[94:97], v[130:133], v[202:205], v[94:97]
	v_mfma_f32_16x16x32_bf16 v[90:93], v[138:141], v[202:205], v[90:93]
	v_mfma_f32_16x16x32_bf16 v[78:81], v[130:133], v[218:221], v[78:81]
	v_mfma_f32_16x16x32_bf16 v[74:77], v[138:141], v[218:221], v[74:77]
	v_mfma_f32_16x16x32_bf16 v[126:129], v[134:137], v[166:169], v[126:129]
	v_mfma_f32_16x16x32_bf16 v[122:125], v[142:145], v[166:169], v[122:125]
	v_mfma_f32_16x16x32_bf16 v[110:113], v[134:137], v[198:201], v[110:113]
	v_mfma_f32_16x16x32_bf16 v[106:109], v[142:145], v[198:201], v[106:109]
	v_mfma_f32_16x16x32_bf16 v[94:97], v[134:137], v[206:209], v[94:97]
	v_mfma_f32_16x16x32_bf16 v[90:93], v[142:145], v[206:209], v[90:93]
	v_mfma_f32_16x16x32_bf16 v[78:81], v[134:137], v[222:225], v[78:81]
	v_mfma_f32_16x16x32_bf16 v[74:77], v[142:145], v[222:225], v[74:77]
	v_mfma_f32_16x16x32_bf16 v[118:121], v[146:149], v[162:165], v[118:121]
	v_mfma_f32_16x16x32_bf16 v[114:117], v[154:157], v[162:165], v[114:117]
	v_mfma_f32_16x16x32_bf16 v[102:105], v[146:149], v[194:197], v[102:105]
	v_mfma_f32_16x16x32_bf16 v[98:101], v[154:157], v[194:197], v[98:101]
	v_mfma_f32_16x16x32_bf16 v[86:89], v[146:149], v[202:205], v[86:89]
	v_mfma_f32_16x16x32_bf16 v[82:85], v[154:157], v[202:205], v[82:85]
	v_mfma_f32_16x16x32_bf16 v[70:73], v[146:149], v[218:221], v[70:73]
	v_mfma_f32_16x16x32_bf16 v[66:69], v[154:157], v[218:221], v[66:69]
	v_mfma_f32_16x16x32_bf16 v[118:121], v[150:153], v[166:169], v[118:121]
	v_mfma_f32_16x16x32_bf16 v[114:117], v[158:161], v[166:169], v[114:117]
	v_mfma_f32_16x16x32_bf16 v[102:105], v[150:153], v[198:201], v[102:105]
	v_mfma_f32_16x16x32_bf16 v[98:101], v[158:161], v[198:201], v[98:101]
	v_mfma_f32_16x16x32_bf16 v[86:89], v[150:153], v[206:209], v[86:89]
	v_mfma_f32_16x16x32_bf16 v[82:85], v[158:161], v[206:209], v[82:85]
	v_mfma_f32_16x16x32_bf16 v[70:73], v[150:153], v[222:225], v[70:73]
	v_mfma_f32_16x16x32_bf16 v[66:69], v[158:161], v[222:225], v[66:69]
	s_setprio 0
	s_barrier
	s_add_u32 s18, s56, 0x80
	s_addc_u32 s19, s57, 0
	s_add_i32 s83, s83, s25
	ds_read_b128 v[162:165], v216 offset:49152
	ds_read_b128 v[166:169], v216 offset:50176
	ds_read_b128 v[194:197], v216 offset:51200
	ds_read_b128 v[198:201], v216 offset:52224
	ds_read_b128 v[202:205], v216 offset:53248
	ds_read_b128 v[206:209], v216 offset:54272
	ds_read_b128 v[218:221], v216 offset:55296
	ds_read_b128 v[222:225], v216 offset:56320
	s_mov_b32 m0, s83
	v_lshl_add_u64 v[210:211], s[18:19], 0, v[172:173]
	global_load_lds_dwordx4 v[210:211], off
	s_add_i32 m0, s83, 0x2000
	v_lshl_add_u64 v[210:211], s[18:19], 0, v[170:171]
	s_add_u32 s18, s56, 0x40080
	s_addc_u32 s19, s57, 0
	s_add_i32 s56, s84, s25
	global_load_lds_dwordx4 v[210:211], off
	s_mov_b32 m0, s56
	v_lshl_add_u64 v[210:211], s[18:19], 0, v[172:173]
	global_load_lds_dwordx4 v[210:211], off
	v_lshl_add_u64 v[210:211], s[18:19], 0, v[170:171]
	s_add_i32 m0, s56, 0x2000
	s_nop 0
	global_load_lds_dwordx4 v[210:211], off
	s_mov_b32 m0, s68
	v_lshl_add_u64 v[210:211], s[26:27], 0, v[172:173]
	global_load_lds_dwordx4 v[210:211], off
	v_lshl_add_u64 v[210:211], s[26:27], 0, v[170:171]
	s_mov_b32 m0, s69
	s_nop 0
	global_load_lds_dwordx4 v[210:211], off
	s_waitcnt vmcnt(8)
	s_waitcnt lgkmcnt(0)
	s_barrier
	s_setprio 1
	s_waitcnt lgkmcnt(0)
	s_cmp_lg_u32 s100, 0
	s_cbranch_scc1 .Lh9_m1
	v_mfma_f32_16x16x32_bf16 v[62:65], v[130:133], v[162:165], v[62:65]
	v_mfma_f32_16x16x32_bf16 v[58:61], v[138:141], v[162:165], v[58:61]
	v_mfma_f32_16x16x32_bf16 v[46:49], v[130:133], v[194:197], v[46:49]
	v_mfma_f32_16x16x32_bf16 v[42:45], v[138:141], v[194:197], v[42:45]
	v_mfma_f32_16x16x32_bf16 v[30:33], v[130:133], v[202:205], v[30:33]
	v_mfma_f32_16x16x32_bf16 v[26:29], v[138:141], v[202:205], v[26:29]
	v_mfma_f32_16x16x32_bf16 v[14:17], v[130:133], v[218:221], v[14:17]
	v_mfma_f32_16x16x32_bf16 v[10:13], v[138:141], v[218:221], v[10:13]
	v_mfma_f32_16x16x32_bf16 v[62:65], v[134:137], v[166:169], v[62:65]
	v_mfma_f32_16x16x32_bf16 v[58:61], v[142:145], v[166:169], v[58:61]
	v_mfma_f32_16x16x32_bf16 v[46:49], v[134:137], v[198:201], v[46:49]
	v_mfma_f32_16x16x32_bf16 v[42:45], v[142:145], v[198:201], v[42:45]
	v_mfma_f32_16x16x32_bf16 v[30:33], v[134:137], v[206:209], v[30:33]
	v_mfma_f32_16x16x32_bf16 v[26:29], v[142:145], v[206:209], v[26:29]
	v_mfma_f32_16x16x32_bf16 v[14:17], v[134:137], v[222:225], v[14:17]
	v_mfma_f32_16x16x32_bf16 v[10:13], v[142:145], v[222:225], v[10:13]
	v_mfma_f32_16x16x32_bf16 v[54:57], v[146:149], v[162:165], v[54:57]
	v_mfma_f32_16x16x32_bf16 v[50:53], v[154:157], v[162:165], v[50:53]
	v_mfma_f32_16x16x32_bf16 v[38:41], v[146:149], v[194:197], v[38:41]
	v_mfma_f32_16x16x32_bf16 v[34:37], v[154:157], v[194:197], v[34:37]
	v_mfma_f32_16x16x32_bf16 v[22:25], v[146:149], v[202:205], v[22:25]
	v_mfma_f32_16x16x32_bf16 v[18:21], v[154:157], v[202:205], v[18:21]
	v_mfma_f32_16x16x32_bf16 v[6:9], v[146:149], v[218:221], v[6:9]
	v_mfma_f32_16x16x32_bf16 v[2:5], v[154:157], v[218:221], v[2:5]
	v_mfma_f32_16x16x32_bf16 v[54:57], v[150:153], v[166:169], v[54:57]
	v_mfma_f32_16x16x32_bf16 v[50:53], v[158:161], v[166:169], v[50:53]
	v_mfma_f32_16x16x32_bf16 v[38:41], v[150:153], v[198:201], v[38:41]
	v_mfma_f32_16x16x32_bf16 v[34:37], v[158:161], v[198:201], v[34:37]
	v_mfma_f32_16x16x32_bf16 v[22:25], v[150:153], v[206:209], v[22:25]
	v_mfma_f32_16x16x32_bf16 v[18:21], v[158:161], v[206:209], v[18:21]
	v_mfma_f32_16x16x32_bf16 v[6:9], v[150:153], v[222:225], v[6:9]
	v_mfma_f32_16x16x32_bf16 v[2:5], v[158:161], v[222:225], v[2:5]
.Lh9_m1:
	s_setprio 0
	s_barrier
	s_add_u32 s78, s78, 0x100
	s_addc_u32 s79, s79, 0
	s_add_u32 s80, s80, 0x100
	s_addc_u32 s81, s81, 0
	s_cmp_ge_i32 s82, s67
	s_mov_b32 s18, s82
	s_cbranch_scc0 .LBB0_253
	s_mov_b32 s72, 0x18000
	s_mov_b32 s78, 0x1a000
	s_mov_b32 s79, 0x8000
	s_mov_b32 s80, 0x1e000
	s_mov_b32 s81, 0xc000
	s_mov_b32 s82, 0xe000
	s_mov_b32 s83, 0xb000
	s_mov_b32 s84, 0x4ffff
	s_mov_b32 s85, 0x66666667
	s_mov_b32 s86, 0x1f000

.LBB0_257:
	v_mov_b32_e32 v0, v179
	s_cmp_eq_u32 s100, 2
	s_cselect_b32 vcc_lo, 0x80, 0
	s_add_i32 s18, s44, -16
	s_lshr_b32 s18, s18, 3
	v_and_b32_e32 v212, 15, v0
	v_bfe_u32 v214, v0, 4, 2
	v_ashrrev_i32_e32 v130, 2, v0
	v_lshrrev_b32_e32 v0, 1, v0
	s_add_i32 s18, s18, 1
	v_and_b32_e32 v130, 0xffffffc0, v130
	v_and_b32_e32 v0, 0x60, v0
	s_cmp_gt_i32 s44, 15
	v_lshl_add_u32 v146, s44, 8, v130
	v_add_u32_e32 v146, vcc_lo, v146
	v_lshl_or_b32 v0, s45, 8, v0
	s_cselect_b32 s18, s18, 0
	v_lshl_or_b32 v130, v214, 2, v0
	s_mul_hi_u32 s19, s18, 0x6000
	s_mulk_i32 s18, 0x6000
	v_or_b32_e32 v210, v146, v212
	s_add_u32 s18, s62, s18
	v_ashrrev_i32_e32 v131, 31, v130
	v_lshlrev_b32_e32 v0, 4, v214
	v_ashrrev_i32_e32 v211, 31, v210
	s_addc_u32 s19, s63, s19
	v_lshlrev_b64 v[194:195], 2, v[130:131]
	v_lshl_add_u64 v[146:147], s[30:31], 0, v[0:1]
	v_lshlrev_b64 v[148:149], 6, v[210:211]
	v_or_b32_e32 v208, 16, v210
	v_lshl_add_u64 v[130:131], s[18:19], 0, v[194:195]
	v_lshl_add_u64 v[148:149], v[146:147], 0, v[148:149]
	v_ashrrev_i32_e32 v209, 31, v208
	global_load_dwordx4 v[142:145], v[130:131], off
	global_load_dwordx4 v[138:141], v[130:131], off offset:64
	global_load_dwordx4 v[134:137], v[130:131], off offset:512
	s_nop 0
	global_load_dwordx4 v[130:133], v[130:131], off offset:576
	v_or_b32_e32 v206, 32, v210
	global_load_dwordx4 v[220:223], v[148:149], off
	v_lshlrev_b64 v[148:149], 6, v[208:209]
	v_lshl_add_u64 v[148:149], v[146:147], 0, v[148:149]
	global_load_dwordx4 v[224:227], v[148:149], off
	v_ashrrev_i32_e32 v207, 31, v206
	v_lshlrev_b64 v[148:149], 6, v[206:207]
	v_or_b32_e32 v204, 48, v210
	v_lshl_add_u64 v[148:149], v[146:147], 0, v[148:149]
	v_ashrrev_i32_e32 v205, 31, v204
	global_load_dwordx4 v[166:169], v[148:149], off
	v_lshlrev_b64 v[148:149], 6, v[204:205]
	v_lshl_add_u64 v[148:149], v[146:147], 0, v[148:149]
	global_load_dwordx4 v[162:165], v[148:149], off
	v_add_u32_e32 v202, 0x80, v210
	v_ashrrev_i32_e32 v203, 31, v202
	v_lshlrev_b64 v[148:149], 6, v[202:203]
	v_add_u32_e32 v200, 0x90, v210
	v_lshl_add_u64 v[148:149], v[146:147], 0, v[148:149]
	v_ashrrev_i32_e32 v201, 31, v200
	global_load_dwordx4 v[158:161], v[148:149], off
	v_lshlrev_b64 v[148:149], 6, v[200:201]
	v_lshl_add_u64 v[148:149], v[146:147], 0, v[148:149]
	global_load_dwordx4 v[154:157], v[148:149], off
	v_add_u32_e32 v198, 0xa0, v210
	v_ashrrev_i32_e32 v199, 31, v198
	v_lshlrev_b64 v[148:149], 6, v[198:199]
	v_add_u32_e32 v196, 0xb0, v210
	v_lshl_add_u64 v[148:149], v[146:147], 0, v[148:149]
	v_ashrrev_i32_e32 v197, 31, v196
	global_load_dwordx4 v[150:153], v[148:149], off
	v_lshlrev_b64 v[148:149], 6, v[196:197]
	v_lshl_add_u64 v[146:147], v[146:147], 0, v[148:149]
	global_load_dwordx4 v[146:149], v[146:147], off
	v_lshlrev_b32_e32 v0, 6, v214
	v_lshlrev_b32_e32 v212, 2, v212
	v_bitop3_b32 v218, v0, 64, v212 bitop3:0x36
	v_bitop3_b32 v217, v0, s90, v212 bitop3:0x36
	s_mov_b32 s18, 0x358637bd
	s_waitcnt vmcnt(0)
	v_mov_b32_e32 v214, v221
	v_mov_b32_e32 v215, v222
	v_mov_b32_e32 v221, v223
	v_pk_add_f32 v[214:215], v[214:215], v[220:221]
	v_mov_b32_e32 v220, v225
	v_mov_b32_e32 v221, v226
	v_mov_b32_e32 v225, v227
	v_pk_add_f32 v[220:221], v[220:221], v[224:225]
	v_mov_b32_e32 v223, v214
	v_mov_b32_e32 v222, v220
	v_mov_b32_e32 v214, v221
	v_pk_add_f32 v[214:215], v[222:223], v[214:215]
	ds_bpermute_b32 v221, v218, v215
	ds_bpermute_b32 v220, v218, v214
	s_waitcnt lgkmcnt(0)
	v_pk_add_f32 v[214:215], v[214:215], v[220:221]
	ds_bpermute_b32 v221, v217, v215
	ds_bpermute_b32 v220, v217, v214
	s_waitcnt lgkmcnt(0)
	v_pk_add_f32 v[220:221], v[214:215], v[220:221]
	v_mov_b64_e32 v[214:215], s[18:19]
	v_pk_fma_f32 v[220:221], v[220:221], s[38:39], v[214:215] op_sel_hi:[1,0,0]
	s_mov_b64 s[18:19], -1
	v_mul_f32_e32 v0, 0x4b800000, v221
	v_cmp_gt_f32_e64 s[44:45], s20, v221
	v_cmp_gt_f32_e32 vcc, s20, v220
	s_nop 0
	v_cndmask_b32_e64 v0, v221, v0, s[44:45]
	v_rsq_f32_e32 v0, v0
	v_mov_b32_e32 v221, v168
	v_mov_b32_e32 v168, v163
	v_mov_b32_e32 v163, v165
	v_mul_f32_e32 v212, 0x45800000, v0
	v_cndmask_b32_e64 v212, v0, v212, s[44:45]
	v_mul_f32_e32 v0, 0x4b800000, v220
	v_cndmask_b32_e32 v0, v220, v0, vcc
	v_mov_b32_e32 v220, v167
	v_mov_b32_e32 v167, v169
	v_mov_b32_e32 v169, v164
	v_pk_add_f32 v[166:167], v[220:221], v[166:167]
	v_pk_add_f32 v[162:163], v[168:169], v[162:163]
	v_mov_b32_e32 v165, v166
	v_mov_b32_e32 v164, v162
	v_mov_b32_e32 v166, v163
	v_pk_add_f32 v[162:163], v[164:165], v[166:167]
	ds_bpermute_b32 v165, v218, v163
	ds_bpermute_b32 v164, v218, v162
	v_mov_b32_e32 v166, v159
	v_mov_b32_e32 v167, v160
	v_mov_b32_e32 v159, v161
	v_mov_b32_e32 v160, v155
	v_mov_b32_e32 v161, v156
	v_mov_b32_e32 v155, v157
	v_pk_add_f32 v[158:159], v[166:167], v[158:159]
	v_pk_add_f32 v[154:155], v[160:161], v[154:155]
	s_waitcnt lgkmcnt(0)
	v_pk_add_f32 v[162:163], v[162:163], v[164:165]
	v_mov_b32_e32 v156, v154
	v_mov_b32_e32 v157, v158
	v_mov_b32_e32 v158, v155
	ds_bpermute_b32 v165, v217, v163
	ds_bpermute_b32 v164, v217, v162
	v_pk_add_f32 v[154:155], v[156:157], v[158:159]
	ds_bpermute_b32 v157, v218, v155
	ds_bpermute_b32 v156, v218, v154
	v_mov_b32_e32 v158, v151
	v_mov_b32_e32 v159, v152
	v_mov_b32_e32 v151, v153
	v_mov_b32_e32 v152, v147
	v_mov_b32_e32 v153, v148
	v_mov_b32_e32 v147, v149
	s_waitcnt lgkmcnt(2)
	v_pk_add_f32 v[162:163], v[162:163], v[164:165]
	v_pk_add_f32 v[150:151], v[158:159], v[150:151]
	v_pk_add_f32 v[146:147], v[152:153], v[146:147]
	v_pk_fma_f32 v[162:163], v[162:163], s[38:39], v[214:215] op_sel_hi:[1,0,0]
	s_waitcnt lgkmcnt(0)
	v_pk_add_f32 v[154:155], v[154:155], v[156:157]
	v_mov_b32_e32 v148, v146
	v_mov_b32_e32 v149, v150
	v_mov_b32_e32 v150, v147
	v_mul_f32_e32 v164, 0x4b800000, v163
	v_cmp_gt_f32_e64 s[44:45], s20, v163
	ds_bpermute_b32 v157, v217, v155
	ds_bpermute_b32 v156, v217, v154
	v_pk_add_f32 v[146:147], v[148:149], v[150:151]
	v_cndmask_b32_e64 v163, v163, v164, s[44:45]
	ds_bpermute_b32 v149, v218, v147
	ds_bpermute_b32 v148, v218, v146
	v_rsq_f32_e32 v0, v0
	v_rsq_f32_e32 v163, v163
	s_waitcnt lgkmcnt(2)
	v_pk_add_f32 v[154:155], v[154:155], v[156:157]
	v_lshlrev_b64 v[150:151], 12, v[210:211]
	v_mul_f32_e32 v219, 0x45800000, v0
	v_mul_f32_e32 v164, 0x45800000, v163
	v_pk_fma_f32 v[154:155], v[154:155], s[38:39], v[214:215] op_sel_hi:[1,0,0]
	s_waitcnt lgkmcnt(0)
	v_pk_add_f32 v[146:147], v[146:147], v[148:149]
	v_cndmask_b32_e32 v0, v0, v219, vcc
	v_cmp_gt_f32_e32 vcc, s20, v162
	v_cndmask_b32_e64 v164, v163, v164, s[44:45]
	v_mul_f32_e32 v163, 0x4b800000, v162
	v_mul_f32_e32 v156, 0x4b800000, v155
	v_cmp_gt_f32_e64 s[44:45], s20, v155
	ds_bpermute_b32 v149, v217, v147
	ds_bpermute_b32 v148, v217, v146
	v_lshl_add_u64 v[150:151], s[2:3], 0, v[150:151]
	v_cndmask_b32_e32 v162, v162, v163, vcc
	v_cndmask_b32_e64 v155, v155, v156, s[44:45]
	v_lshl_add_u64 v[150:151], v[150:151], 0, v[194:195]
	v_pk_fma_f32 v[116:117], v[116:117], v[212:213], v[132:133] op_sel_hi:[1,0,1]
	v_pk_fma_f32 v[114:115], v[114:115], v[212:213], v[130:131] op_sel_hi:[1,0,1]
	v_rsq_f32_e32 v162, v162
	v_rsq_f32_e32 v155, v155
	global_store_dwordx4 v[150:151], v[114:117], off offset:576
	v_pk_fma_f32 v[100:101], v[100:101], v[0:1], v[132:133] op_sel_hi:[1,0,1]
	v_pk_fma_f32 v[98:99], v[98:99], v[0:1], v[130:131] op_sel_hi:[1,0,1]
	v_lshlrev_b64 v[114:115], 12, v[208:209]
	v_lshl_add_u64 v[114:115], s[2:3], 0, v[114:115]
	v_lshl_add_u64 v[114:115], v[114:115], 0, v[194:195]
	s_waitcnt lgkmcnt(0)
	v_pk_add_f32 v[146:147], v[146:147], v[148:149]
	global_store_dwordx4 v[114:115], v[98:101], off offset:576
	v_mul_f32_e32 v163, 0x45800000, v162
	v_mul_f32_e32 v156, 0x45800000, v155
	v_lshlrev_b64 v[98:99], 12, v[206:207]
	v_pk_fma_f32 v[146:147], v[146:147], s[38:39], v[214:215] op_sel_hi:[1,0,0]
	v_lshl_add_u64 v[98:99], s[2:3], 0, v[98:99]
	v_cndmask_b32_e32 v162, v162, v163, vcc
	v_cmp_gt_f32_e32 vcc, s20, v154
	v_cndmask_b32_e64 v156, v155, v156, s[44:45]
	v_mul_f32_e32 v155, 0x4b800000, v154
	v_mul_f32_e32 v148, 0x4b800000, v147
	v_cmp_gt_f32_e64 s[44:45], s20, v147
	v_lshl_add_u64 v[98:99], v[98:99], 0, v[194:195]
	v_pk_fma_f32 v[84:85], v[84:85], v[164:165], v[132:133] op_sel_hi:[1,0,1]
	v_pk_fma_f32 v[82:83], v[82:83], v[164:165], v[130:131] op_sel_hi:[1,0,1]
	v_cndmask_b32_e32 v154, v154, v155, vcc
	v_cndmask_b32_e64 v147, v147, v148, s[44:45]
	global_store_dwordx4 v[98:99], v[82:85], off offset:576
	v_rsq_f32_e32 v154, v154
	v_rsq_f32_e32 v147, v147
	v_lshlrev_b64 v[82:83], 12, v[204:205]
	v_lshl_add_u64 v[82:83], s[2:3], 0, v[82:83]
	v_lshl_add_u64 v[82:83], v[82:83], 0, v[194:195]
	v_pk_fma_f32 v[68:69], v[68:69], v[162:163], v[132:133] op_sel_hi:[1,0,1]
	v_pk_fma_f32 v[66:67], v[66:67], v[162:163], v[130:131] op_sel_hi:[1,0,1]
	global_store_dwordx4 v[82:83], v[66:69], off offset:576
	v_mul_f32_e32 v155, 0x45800000, v154
	v_mul_f32_e32 v148, 0x45800000, v147
	v_lshlrev_b64 v[66:67], 12, v[202:203]
	v_lshl_add_u64 v[66:67], s[2:3], 0, v[66:67]
	v_lshl_add_u64 v[66:67], v[66:67], 0, v[194:195]
	v_pk_fma_f32 v[52:53], v[52:53], v[156:157], v[132:133] op_sel_hi:[1,0,1]
	v_pk_fma_f32 v[50:51], v[50:51], v[156:157], v[130:131] op_sel_hi:[1,0,1]
	v_cndmask_b32_e32 v154, v154, v155, vcc
	v_cmp_gt_f32_e32 vcc, s20, v146
	v_cndmask_b32_e64 v148, v147, v148, s[44:45]
	v_mul_f32_e32 v147, 0x4b800000, v146
	s_cmp_lg_u32 s100, 0
	s_cbranch_scc1 .Lh9_s0
	global_store_dwordx4 v[66:67], v[50:53], off offset:576
.Lh9_s0:
	v_cndmask_b32_e32 v146, v146, v147, vcc
	v_rsq_f32_e32 v146, v146
	v_lshlrev_b64 v[50:51], 12, v[200:201]
	v_lshl_add_u64 v[50:51], s[2:3], 0, v[50:51]
	v_lshl_add_u64 v[50:51], v[50:51], 0, v[194:195]
	v_pk_fma_f32 v[36:37], v[36:37], v[154:155], v[132:133] op_sel_hi:[1,0,1]
	v_pk_fma_f32 v[34:35], v[34:35], v[154:155], v[130:131] op_sel_hi:[1,0,1]
	s_cmp_lg_u32 s100, 0
	s_cbranch_scc1 .Lh9_s1
	global_store_dwordx4 v[50:51], v[34:37], off offset:576
.Lh9_s1:
	v_pk_fma_f32 v[20:21], v[20:21], v[148:149], v[132:133] op_sel_hi:[1,0,1]
	v_pk_fma_f32 v[18:19], v[18:19], v[148:149], v[130:131] op_sel_hi:[1,0,1]
	v_lshlrev_b64 v[34:35], 12, v[198:199]
	v_lshl_add_u64 v[34:35], s[2:3], 0, v[34:35]
	v_lshl_add_u64 v[34:35], v[34:35], 0, v[194:195]
	v_mul_f32_e32 v147, 0x45800000, v146
	s_cmp_lg_u32 s100, 0
	s_cbranch_scc1 .Lh9_s2
	global_store_dwordx4 v[34:35], v[18:21], off offset:576
.Lh9_s2:
	v_cndmask_b32_e32 v146, v146, v147, vcc
	v_pk_fma_f32 v[128:129], v[128:129], v[212:213], v[144:145] op_sel_hi:[1,0,1]
	v_lshlrev_b64 v[18:19], 12, v[196:197]
	v_lshl_add_u64 v[18:19], s[2:3], 0, v[18:19]
	v_pk_fma_f32 v[126:127], v[126:127], v[212:213], v[142:143] op_sel_hi:[1,0,1]
	v_pk_fma_f32 v[124:125], v[124:125], v[212:213], v[140:141] op_sel_hi:[1,0,1]
	v_pk_fma_f32 v[122:123], v[122:123], v[212:213], v[138:139] op_sel_hi:[1,0,1]
	v_pk_fma_f32 v[120:121], v[120:121], v[212:213], v[136:137] op_sel_hi:[1,0,1]
	v_pk_fma_f32 v[118:119], v[118:119], v[212:213], v[134:135] op_sel_hi:[1,0,1]
	v_pk_fma_f32 v[112:113], v[112:113], v[0:1], v[144:145] op_sel_hi:[1,0,1]
	v_pk_fma_f32 v[110:111], v[110:111], v[0:1], v[142:143] op_sel_hi:[1,0,1]
	v_pk_fma_f32 v[108:109], v[108:109], v[0:1], v[140:141] op_sel_hi:[1,0,1]
	v_pk_fma_f32 v[106:107], v[106:107], v[0:1], v[138:139] op_sel_hi:[1,0,1]
	v_pk_fma_f32 v[104:105], v[104:105], v[0:1], v[136:137] op_sel_hi:[1,0,1]
	v_pk_fma_f32 v[102:103], v[102:103], v[0:1], v[134:135] op_sel_hi:[1,0,1]
	v_pk_fma_f32 v[96:97], v[96:97], v[164:165], v[144:145] op_sel_hi:[1,0,1]
	v_pk_fma_f32 v[94:95], v[94:95], v[164:165], v[142:143] op_sel_hi:[1,0,1]
	v_pk_fma_f32 v[92:93], v[92:93], v[164:165], v[140:141] op_sel_hi:[1,0,1]
	v_pk_fma_f32 v[90:91], v[90:91], v[164:165], v[138:139] op_sel_hi:[1,0,1]
	v_pk_fma_f32 v[88:89], v[88:89], v[164:165], v[136:137] op_sel_hi:[1,0,1]
	v_pk_fma_f32 v[86:87], v[86:87], v[164:165], v[134:135] op_sel_hi:[1,0,1]
	v_pk_fma_f32 v[80:81], v[80:81], v[162:163], v[144:145] op_sel_hi:[1,0,1]
	v_pk_fma_f32 v[78:79], v[78:79], v[162:163], v[142:143] op_sel_hi:[1,0,1]
	v_pk_fma_f32 v[76:77], v[76:77], v[162:163], v[140:141] op_sel_hi:[1,0,1]
	v_pk_fma_f32 v[74:75], v[74:75], v[162:163], v[138:139] op_sel_hi:[1,0,1]
	v_pk_fma_f32 v[72:73], v[72:73], v[162:163], v[136:137] op_sel_hi:[1,0,1]
	v_pk_fma_f32 v[70:71], v[70:71], v[162:163], v[134:135] op_sel_hi:[1,0,1]
	v_pk_fma_f32 v[64:65], v[64:65], v[156:157], v[144:145] op_sel_hi:[1,0,1]
	v_pk_fma_f32 v[62:63], v[62:63], v[156:157], v[142:143] op_sel_hi:[1,0,1]
	v_pk_fma_f32 v[60:61], v[60:61], v[156:157], v[140:141] op_sel_hi:[1,0,1]
	v_pk_fma_f32 v[58:59], v[58:59], v[156:157], v[138:139] op_sel_hi:[1,0,1]
	v_pk_fma_f32 v[56:57], v[56:57], v[156:157], v[136:137] op_sel_hi:[1,0,1]
	v_pk_fma_f32 v[54:55], v[54:55], v[156:157], v[134:135] op_sel_hi:[1,0,1]
	v_pk_fma_f32 v[48:49], v[48:49], v[154:155], v[144:145] op_sel_hi:[1,0,1]
	v_pk_fma_f32 v[46:47], v[46:47], v[154:155], v[142:143] op_sel_hi:[1,0,1]
	v_pk_fma_f32 v[44:45], v[44:45], v[154:155], v[140:141] op_sel_hi:[1,0,1]
	v_pk_fma_f32 v[42:43], v[42:43], v[154:155], v[138:139] op_sel_hi:[1,0,1]
	v_pk_fma_f32 v[40:41], v[40:41], v[154:155], v[136:137] op_sel_hi:[1,0,1]
	v_pk_fma_f32 v[38:39], v[38:39], v[154:155], v[134:135] op_sel_hi:[1,0,1]
	v_pk_fma_f32 v[32:33], v[32:33], v[148:149], v[144:145] op_sel_hi:[1,0,1]
	v_pk_fma_f32 v[30:31], v[30:31], v[148:149], v[142:143] op_sel_hi:[1,0,1]
	v_pk_fma_f32 v[28:29], v[28:29], v[148:149], v[140:141] op_sel_hi:[1,0,1]
	v_pk_fma_f32 v[26:27], v[26:27], v[148:149], v[138:139] op_sel_hi:[1,0,1]
	v_pk_fma_f32 v[24:25], v[24:25], v[148:149], v[136:137] op_sel_hi:[1,0,1]
	v_pk_fma_f32 v[22:23], v[22:23], v[148:149], v[134:135] op_sel_hi:[1,0,1]
	v_lshl_add_u64 v[18:19], v[18:19], 0, v[194:195]
	v_pk_fma_f32 v[16:17], v[16:17], v[146:147], v[144:145] op_sel_hi:[1,0,1]
	v_pk_fma_f32 v[14:15], v[14:15], v[146:147], v[142:143] op_sel_hi:[1,0,1]
	v_pk_fma_f32 v[12:13], v[12:13], v[146:147], v[140:141] op_sel_hi:[1,0,1]
	v_pk_fma_f32 v[10:11], v[10:11], v[146:147], v[138:139] op_sel_hi:[1,0,1]
	v_pk_fma_f32 v[8:9], v[8:9], v[146:147], v[136:137] op_sel_hi:[1,0,1]
	v_pk_fma_f32 v[6:7], v[6:7], v[146:147], v[134:135] op_sel_hi:[1,0,1]
	v_pk_fma_f32 v[4:5], v[4:5], v[146:147], v[132:133] op_sel_hi:[1,0,1]
	v_pk_fma_f32 v[2:3], v[2:3], v[146:147], v[130:131] op_sel_hi:[1,0,1]
	s_andn2_b64 vcc, exec, s[42:43]
	global_store_dwordx4 v[150:151], v[126:129], off
	global_store_dwordx4 v[150:151], v[122:125], off offset:64
	global_store_dwordx4 v[150:151], v[118:121], off offset:512
	global_store_dwordx4 v[114:115], v[110:113], off
	global_store_dwordx4 v[114:115], v[106:109], off offset:64
	global_store_dwordx4 v[114:115], v[102:105], off offset:512
	global_store_dwordx4 v[98:99], v[94:97], off
	global_store_dwordx4 v[98:99], v[90:93], off offset:64
	global_store_dwordx4 v[98:99], v[86:89], off offset:512
	global_store_dwordx4 v[82:83], v[78:81], off
	global_store_dwordx4 v[82:83], v[74:77], off offset:64
	global_store_dwordx4 v[82:83], v[70:73], off offset:512
	s_cmp_lg_u32 s100, 0
	s_cbranch_scc1 .Lh9_e
	global_store_dwordx4 v[66:67], v[62:65], off
	global_store_dwordx4 v[66:67], v[58:61], off offset:64
	global_store_dwordx4 v[66:67], v[54:57], off offset:512
	global_store_dwordx4 v[50:51], v[46:49], off
	global_store_dwordx4 v[50:51], v[42:45], off offset:64
	global_store_dwordx4 v[50:51], v[38:41], off offset:512
	global_store_dwordx4 v[34:35], v[30:33], off
	global_store_dwordx4 v[34:35], v[26:29], off offset:64
	global_store_dwordx4 v[34:35], v[22:25], off offset:512
	global_store_dwordx4 v[18:19], v[14:17], off
	global_store_dwordx4 v[18:19], v[10:13], off offset:64
	global_store_dwordx4 v[18:19], v[6:9], off offset:512
	global_store_dwordx4 v[18:19], v[2:5], off offset:576
.Lh9_e:
	s_cbranch_vccnz .LBB0_248
	s_andn2_b64 vcc, exec, s[0:1]
	s_cbranch_vccnz .LBB0_247
	s_barrier
	s_branch .LBB0_247

	.amdhsa_kernel _Z10fwd_kernel6Params
		.amdhsa_group_segment_fixed_size 0
		.amdhsa_private_segment_fixed_size 0
		.amdhsa_kernarg_size 512
		.amdhsa_user_sgpr_count 2
		.amdhsa_user_sgpr_dispatch_ptr 0
		.amdhsa_user_sgpr_queue_ptr 0
		.amdhsa_user_sgpr_kernarg_segment_ptr 1
		.amdhsa_user_sgpr_dispatch_id 0
		.amdhsa_user_sgpr_kernarg_preload_length 0
		.amdhsa_user_sgpr_kernarg_preload_offset 0
		.amdhsa_user_sgpr_private_segment_size 0
		.amdhsa_uses_dynamic_stack 0
		.amdhsa_enable_private_segment 0
		.amdhsa_system_sgpr_workgroup_id_x 1
		.amdhsa_system_sgpr_workgroup_id_y 0
		.amdhsa_system_sgpr_workgroup_id_z 0
		.amdhsa_system_sgpr_workgroup_info 0
		.amdhsa_system_vgpr_workitem_id 2
		.amdhsa_next_free_vgpr 256
		.amdhsa_next_free_sgpr 102
		.amdhsa_accum_offset 256
		.amdhsa_reserve_vcc 1
		.amdhsa_float_round_mode_32 0
		.amdhsa_float_round_mode_16_64 0
		.amdhsa_float_denorm_mode_32 3
		.amdhsa_float_denorm_mode_16_64 3
		.amdhsa_dx10_clamp 1
		.amdhsa_ieee_mode 1
		.amdhsa_fp16_overflow 0
		.amdhsa_tg_split 0
		.amdhsa_exception_fp_ieee_invalid_op 0
		.amdhsa_exception_fp_denorm_src 0
		.amdhsa_exception_fp_ieee_div_zero 0
		.amdhsa_exception_fp_ieee_overflow 0
		.amdhsa_exception_fp_ieee_underflow 0
		.amdhsa_exception_fp_ieee_inexact 0
		.amdhsa_exception_int_div_zero 0
	.end_amdhsa_kernel

amdhsa.kernels:
  - .agpr_count:     0
    .args:
      - .offset:         0
        .size:           256
        .value_kind:     by_value
      - .offset:         256
        .size:           4
        .value_kind:     hidden_block_count_x
      - .offset:         260
        .size:           4
        .value_kind:     hidden_block_count_y
      - .offset:         264
        .size:           4
        .value_kind:     hidden_block_count_z
      - .offset:         268
        .size:           2
        .value_kind:     hidden_group_size_x
      - .offset:         270
        .size:           2
        .value_kind:     hidden_group_size_y
      - .offset:         272
        .size:           2
        .value_kind:     hidden_group_size_z
      - .offset:         274
        .size:           2
        .value_kind:     hidden_remainder_x
      - .offset:         276
        .size:           2
        .value_kind:     hidden_remainder_y
      - .offset:         278
        .size:           2
        .value_kind:     hidden_remainder_z
      - .offset:         296
        .size:           8
        .value_kind:     hidden_global_offset_x
      - .offset:         304
        .size:           8
        .value_kind:     hidden_global_offset_y
      - .offset:         312
        .size:           8
        .value_kind:     hidden_global_offset_z
      - .offset:         320
        .size:           2
        .value_kind:     hidden_grid_dims
      - .offset:         344
        .size:           8
        .value_kind:     hidden_multigrid_sync_arg
      - .offset:         376
        .size:           4
        .value_kind:     hidden_dynamic_lds_size
    .group_segment_fixed_size: 0
    .kernarg_segment_align: 8
    .kernarg_segment_size: 512
    .language:       OpenCL C
    .language_version:
      - 2
      - 0
    .max_flat_workgroup_size: 512
    .name:           _Z10fwd_kernel6Params
    .private_segment_fixed_size: 0
    .sgpr_count:     108
    .sgpr_spill_count: 132
    .symbol:         _Z10fwd_kernel6Params.kd
    .uniform_work_group_size: 1
    .uses_dynamic_stack: false
    .vgpr_count:     256
    .vgpr_spill_count: 0
    .wavefront_size: 64
